# attention unmasked scores via float distance (same roundings) + filter-spectra k-loop relaid out: 4 lanes per H3 row, 64 FMA + 8 quad_perm DPP adds per 16 rows
# speedup vs baseline: 1.1305x; 1.0087x over previous
; #define LAS __attribute__((address_space(3)))
; DEVQ void attn_unit(const bf16* qkv, bf16* O, const float* sinkp, LAS unsigned char* lds, int mb, int L, int t0, int kvh) {
;     ...
;         for (int tile = 0; tile < 13; ++tile) {
;             if (tile != 0 && (tile < jlo || tile >= jhi)) continue;
;             f32x16 st;
; #pragma unroll
;             for (int i = 0; i < 16; ++i) st[i] = 0.f;
;             { const LAS bf16* kb = Ks + (tile * 32 + r) * ATT_KSTR + hh * 8;
; #pragma unroll
;               for (int ks = 0; ks < 4; ++ks) { const bf16x8 kf = *(const LAS bf16x8*)(kb + ks * 16); st = __builtin_amdgcn_mfma_f32_32x32x16_bf16(kf, qf[ks], st, 0, 0, 0); } }
;             const int sbase = tile == 0 ? 0 : t0 - 128 + (tile - 1) * 32;
;             const int dq = tq - sbase;
;             const bool need_mask = tile == 0 || tile == jlo || tile == jhi - 1 || sbase < 16 || sbase + 32 > L;
;             float p[16]; float tmax = -INFINITY;
;             if (!need_mask) {
; #pragma unroll
;                 for (int i = 0; i < 16; ++i) { const int cr = (i & 3) + 8 * (i >> 2) + 4 * hh; const int dd = dq - cr; const float dist = (float)(dd < 0 ? -dd : dd);
;                     const float v = st[i] * sc2 - slope2 * dist; p[i] = v; tmax = fmaxf(tmax, v); }
.LBB0_118:
	s_add_i32 s2, s6, 1
	v_cmp_gt_i32_e32 vcc, s2, v92
	v_cmp_lt_i32_e64 s[0:1], s2, v105
	s_and_b64 s[0:1], vcc, s[0:1]
	s_and_saveexec_b64 s[12:13], s[0:1]
	s_cbranch_execz .LBB0_126
	v_add_u32_e32 v64, 0, v110
	ds_read_b128 v[32:35], v64
	ds_read_b128 v[76:79], v64 offset:32
	s_add_i32 s7, s90, s21
	s_add_i32 s3, s7, 0xffffff10
	v_cmp_eq_u32_e64 s[0:1], s6, v92
	s_waitcnt lgkmcnt(1)
	v_mfma_f32_32x32x16_bf16 v[32:47], v[32:35], v[48:51], 0
	v_cmp_ne_u32_e32 vcc, s6, v92
	s_waitcnt lgkmcnt(0)
	v_mfma_f32_32x32x16_bf16 v[32:47], v[76:79], v[52:55], v[32:47]
	ds_read_b128 v[76:79], v64 offset:64
	ds_read_b128 v[80:83], v64 offset:96
	s_waitcnt lgkmcnt(1)
	v_mfma_f32_32x32x16_bf16 v[32:47], v[76:79], v[56:59], v[32:47]
	s_waitcnt lgkmcnt(0)
	v_mfma_f32_32x32x16_bf16 v[32:47], v[80:83], v[60:63], v[32:47]
	s_and_saveexec_b64 s[4:5], vcc
	s_cbranch_execz .LBB0_123
	s_cmp_gt_i32 s3, 15
	s_cselect_b64 s[14:15], -1, 0
	s_addk_i32 s7, 0xff30
	s_cmp_le_i32 s7, s59
	v_cmp_ne_u32_e32 vcc, s6, v108
	s_cselect_b64 s[6:7], -1, 0
	s_and_b64 s[6:7], s[14:15], s[6:7]
	s_and_b64 s[18:19], vcc, s[6:7]
	s_mov_b64 s[14:15], -1
	s_and_saveexec_b64 s[6:7], s[18:19]
	s_cbranch_execz .LBB0_122
	v_add_u32_e32 v64, s21, v101
	v_add_u32_e32 v76, 27, v109
	v_sub_u32_e32 v78, 0xffffffe5, v109
	v_add_u32_e32 v64, 0xffffff10, v64
	v_add_u32_e32 v77, 26, v109
	v_max_i32_e32 v76, v76, v78
	v_sub_u32_e32 v78, 0xffffffe6, v109
	v_max_i32_e32 v77, v77, v78
	v_sub_u32_e32 v78, v75, v64
	v_sub_u32_e32 v64, v74, v64
	v_sub_u32_e32 v79, 0, v64
	v_max_i32_e32 v64, v64, v79
	v_sub_u32_e32 v79, 0, v78
	v_cvt_f32_u32_e32 v77, v77
	v_cvt_f32_u32_e32 v76, v76
	v_max_i32_e32 v78, v78, v79
	v_cvt_f32_u32_e32 v79, v78
	v_cvt_f32_u32_e32 v78, v64
	v_pk_mul_f32 v[76:77], v[70:71], v[76:77]
	s_mov_b32 s14, 0x3e38aa3b
	v_pk_fma_f32 v[76:77], v[32:33], s[14:15], v[76:77] op_sel_hi:[1,0,1] neg_lo:[0,0,1] neg_hi:[0,0,1]
	v_pk_mul_f32 v[78:79], v[70:71], v[78:79]
	v_max3_f32 v80, v76, s42, v77
	v_pk_fma_f32 v[78:79], v[34:35], s[14:15], v[78:79] op_sel_hi:[1,0,1] neg_lo:[0,0,1] neg_hi:[0,0,1]
	v_add_u32_e32 v64, 19, v109
	v_max3_f32 v86, v80, v78, v79
	s_xor_b64 s[14:15], exec, -1
	v_cvt_f32_i32_e32 v117, v109
	v_add_f32_e32 v118, 0x41980000, v117
	v_mul_f32_e64 v120, v65, |v118|
	v_mul_f32_e32 v119, v130, v36
	v_sub_f32_e32 v80, v119, v120
	v_add_f32_e32 v118, 0x41900000, v117
	v_mul_f32_e64 v120, v65, |v118|
	v_mul_f32_e32 v119, v130, v37
	v_sub_f32_e32 v81, v119, v120
	v_max3_f32 v64, v86, v80, v81
	v_add_f32_e32 v118, 0x41880000, v117
	v_mul_f32_e64 v120, v65, |v118|
	v_mul_f32_e32 v119, v130, v38
	v_sub_f32_e32 v82, v119, v120
	v_add_f32_e32 v118, 0x41800000, v117
	v_mul_f32_e64 v120, v65, |v118|
	v_mul_f32_e32 v119, v130, v39
	v_sub_f32_e32 v83, v119, v120
	v_max3_f32 v64, v64, v82, v83
	v_add_f32_e32 v118, 0x41300000, v117
	v_mul_f32_e64 v120, v65, |v118|
	v_mul_f32_e32 v119, v130, v40
	v_sub_f32_e32 v84, v119, v120
	v_add_f32_e32 v118, 0x41200000, v117
	v_mul_f32_e64 v120, v65, |v118|
	v_mul_f32_e32 v119, v130, v41
	v_sub_f32_e32 v85, v119, v120
	v_max3_f32 v64, v64, v84, v85
	v_add_f32_e32 v118, 0x41100000, v117
	v_mul_f32_e64 v120, v65, |v118|
	v_mul_f32_e32 v119, v130, v42
	v_sub_f32_e32 v86, v119, v120
	v_add_f32_e32 v118, 0x41000000, v117
	v_mul_f32_e64 v120, v65, |v118|
	v_mul_f32_e32 v119, v130, v43
	v_sub_f32_e32 v87, v119, v120
	v_max3_f32 v64, v64, v86, v87
	v_add_f32_e32 v118, 0x40400000, v117
	v_mul_f32_e64 v120, v65, |v118|
	v_mul_f32_e32 v119, v130, v44
	v_sub_f32_e32 v88, v119, v120
	v_add_f32_e32 v118, 2.0, v117
	v_mul_f32_e64 v120, v65, |v118|
	v_mul_f32_e32 v119, v130, v45
	v_sub_f32_e32 v89, v119, v120
	v_max3_f32 v64, v64, v88, v89
	v_add_f32_e32 v118, 1.0, v117
	v_mul_f32_e64 v120, v65, |v118|
	v_mul_f32_e32 v119, v130, v46
	v_sub_f32_e32 v90, v119, v120
	v_mul_f32_e64 v120, v65, |v117|
	v_mul_f32_e32 v119, v130, v47
	v_sub_f32_e32 v91, v119, v120
	v_max3_f32 v64, v64, v90, v91

; template <int L, int N> DEVQ void filt_item(const Params& P, LAS unsigned char* lds, const float* H3v, int d, cf* specd, float* cornerd) {
;     ...
;     const float delta = fabsf(MIN_DECAY + (float)d * ((MAX_DECAY - MIN_DECAY) / 1023.0f));
;     const float invN = 1.0f / (float)N;
;     for (int k = tid; k < L; k += NTHR) {
;         asm volatile("" ::: "memory");
;         const f32x4* hr = (const f32x4*)(H3v + (size_t)k * 64);
;         f32x4 acc = (f32x4){0.f, 0.f, 0.f, 0.f};
;         f32x4 hv[16];
; #pragma unroll
;         for (int i4 = 0; i4 < 16; ++i4) hv[i4] = hr[i4];
; #pragma unroll
;         for (int i4 = 0; i4 < 16; ++i4) { if ((i4 & 3) == 0) asm volatile("" ::: "memory");
;             acc += hv[i4].x * wc4[4 * i4] + hv[i4].y * wc4[4 * i4 + 1] + hv[i4].z * wc4[4 * i4 + 2] + hv[i4].w * wc4[4 * i4 + 3]; }
.LBB0_588:
	s_or_b64 exec, exec, s[0:1]
	v_cmp_gt_i32_e32 vcc, s16, v64
	s_waitcnt lgkmcnt(0)
	s_barrier
	s_and_saveexec_b64 s[0:1], vcc
	s_cbranch_execz .LBB0_597
	s_waitcnt vmcnt(0)
	v_cvt_f32_i32_e32 v2, s10
	v_readlane_b32 s2, v253, 41
	v_lshlrev_b64 v[0:1], 8, v[64:65]
	v_mov_b32_e32 v3, 0xc0447cbd
	v_lshl_add_u32 v72, v64, 2, s2
	v_readlane_b32 s2, v255, 40
	v_readlane_b32 s3, v255, 41
	v_sub_u32_e32 v73, 0x2000, v64
	v_fmamk_f32 v74, v2, 0xbc44ade8, v3
	v_lshl_add_u64 v[66:67], s[2:3], 0, v[0:1]
	s_mov_b64 s[12:13], 0
	v_mov_b32_e32 v75, v64
	v_mbcnt_lo_u32_b32 v193, -1, 0
	v_mbcnt_hi_u32_b32 v193, -1, v193
	v_lshrrev_b32_e32 v246, 2, v193
	v_and_b32_e32 v247, 3, v193
	v_lshlrev_b32_e32 v248, 8, v246
	v_lshl_add_u32 v248, v247, 4, v248
	v_lshlrev_b32_e32 v249, 8, v193
	v_sub_u32_e32 v248, v248, v249
	v_add_u32_e32 v250, 0x1000, v248
	v_ashrrev_i32_e32 v251, 31, v250
	v_lshl_add_u32 v248, v247, 6, 0
	v_add_u32_e32 v248, 0x20000, v248
	ds_read_b128 v[148:151], v248
	ds_read_b128 v[154:157], v248 offset:16
	ds_read_b128 v[158:161], v248 offset:32
	ds_read_b128 v[162:165], v248 offset:48
	ds_read_b128 v[194:197], v248 offset:256
	ds_read_b128 v[198:201], v248 offset:272
	ds_read_b128 v[202:205], v248 offset:288
	ds_read_b128 v[210:213], v248 offset:304
	ds_read_b128 v[214:217], v248 offset:512
	ds_read_b128 v[218:221], v248 offset:528
	ds_read_b128 v[222:225], v248 offset:544
	ds_read_b128 v[226:229], v248 offset:560
	ds_read_b128 v[230:233], v248 offset:768
	ds_read_b128 v[234:237], v248 offset:784
	ds_read_b128 v[238:241], v248 offset:800
	ds_read_b128 v[242:245], v248 offset:816
	v_lshrrev_b32_e32 v249, 6, v64
	v_cmp_lt_u32_e64 s[2:3], 5, v249
	v_lshl_add_u32 v249, v249, 10, 0
	v_mov_b32_e32 v247, 0x400
	v_add_u32_e32 v249, 0x20800, v249
	v_cndmask_b32_e64 v247, 0, v247, s[2:3]
	v_add_u32_e32 v249, v249, v247
	v_lshl_add_u32 v153, v246, 4, v249
	v_lshl_add_u32 v193, v193, 4, v249
	s_waitcnt lgkmcnt(0)
	s_branch .LBB0_591

; template <int L, int N> DEVQ void filt_item(const Params& P, LAS unsigned char* lds, const float* H3v, int d, cf* specd, float* cornerd) {
;     ...
;     for (int k = tid; k < L; k += NTHR) {
;         asm volatile("" ::: "memory");
;         const f32x4* hr = (const f32x4*)(H3v + (size_t)k * 64);
;         f32x4 acc = (f32x4){0.f, 0.f, 0.f, 0.f};
;         f32x4 hv[16];
; #pragma unroll
;         for (int i4 = 0; i4 < 16; ++i4) hv[i4] = hr[i4];
; #pragma unroll
;         for (int i4 = 0; i4 < 16; ++i4) { if ((i4 & 3) == 0) asm volatile("" ::: "memory");
;             acc += hv[i4].x * wc4[4 * i4] + hv[i4].y * wc4[4 * i4 + 1] + hv[i4].z * wc4[4 * i4 + 2] + hv[i4].w * wc4[4 * i4 + 3]; }
.LBB0_591:
	s_mov_b64 s[14:15], exec
	s_mov_b64 exec, -1
	v_lshl_add_u64 v[180:181], v[66:67], 0, v[250:251]
	v_add_co_u32_e32 v206, vcc, 0x2000, v180
	s_nop 1
	v_addc_co_u32_e32 v207, vcc, 0, v181, vcc
	global_load_dwordx4 v[0:3], v[180:181], off offset:-4096
	global_load_dwordx4 v[4:7], v[180:181], off offset:-4032
	global_load_dwordx4 v[8:11], v[180:181], off offset:-3968
	global_load_dwordx4 v[12:15], v[180:181], off offset:-3904
	global_load_dwordx4 v[16:19], v[180:181], off offset:0
	global_load_dwordx4 v[20:23], v[180:181], off offset:64
	global_load_dwordx4 v[24:27], v[180:181], off offset:128
	global_load_dwordx4 v[28:31], v[180:181], off offset:192
	global_load_dwordx4 v[32:35], v[206:207], off offset:-4096
	global_load_dwordx4 v[36:39], v[206:207], off offset:-4032
	global_load_dwordx4 v[40:43], v[206:207], off offset:-3968
	global_load_dwordx4 v[44:47], v[206:207], off offset:-3904
	global_load_dwordx4 v[48:51], v[206:207], off offset:0
	global_load_dwordx4 v[52:55], v[206:207], off offset:64
	global_load_dwordx4 v[56:59], v[206:207], off offset:128
	global_load_dwordx4 v[60:63], v[206:207], off offset:192
	s_mov_b32 s2, 0x11111111
	s_mov_b32 s3, 0x11111111
	s_waitcnt vmcnt(12)
	v_mul_f32_e32 v246, v0, v148
	v_mul_f32_e32 v247, v0, v149
	v_mul_f32_e32 v248, v0, v150
	v_mul_f32_e32 v249, v0, v151
	v_fmac_f32_e32 v246, v1, v154
	v_fmac_f32_e32 v247, v1, v155
	v_fmac_f32_e32 v248, v1, v156
	v_fmac_f32_e32 v249, v1, v157
	v_fmac_f32_e32 v246, v2, v158
	v_fmac_f32_e32 v247, v2, v159
	v_fmac_f32_e32 v248, v2, v160
	v_fmac_f32_e32 v249, v2, v161
	v_fmac_f32_e32 v246, v3, v162
	v_fmac_f32_e32 v247, v3, v163
	v_fmac_f32_e32 v248, v3, v164
	v_fmac_f32_e32 v249, v3, v165
	v_fmac_f32_e32 v246, v4, v194
	v_fmac_f32_e32 v247, v4, v195
	v_fmac_f32_e32 v248, v4, v196
	v_fmac_f32_e32 v249, v4, v197
	v_fmac_f32_e32 v246, v5, v198
	v_fmac_f32_e32 v247, v5, v199
	v_fmac_f32_e32 v248, v5, v200
	v_fmac_f32_e32 v249, v5, v201
	v_fmac_f32_e32 v246, v6, v202
	v_fmac_f32_e32 v247, v6, v203
	v_fmac_f32_e32 v248, v6, v204
	v_fmac_f32_e32 v249, v6, v205
	v_fmac_f32_e32 v246, v7, v210
	v_fmac_f32_e32 v247, v7, v211
	v_fmac_f32_e32 v248, v7, v212
	v_fmac_f32_e32 v249, v7, v213
	v_fmac_f32_e32 v246, v8, v214
	v_fmac_f32_e32 v247, v8, v215
	v_fmac_f32_e32 v248, v8, v216
	v_fmac_f32_e32 v249, v8, v217
	v_fmac_f32_e32 v246, v9, v218
	v_fmac_f32_e32 v247, v9, v219
	v_fmac_f32_e32 v248, v9, v220
	v_fmac_f32_e32 v249, v9, v221
	v_fmac_f32_e32 v246, v10, v222
	v_fmac_f32_e32 v247, v10, v223
	v_fmac_f32_e32 v248, v10, v224
	v_fmac_f32_e32 v249, v10, v225
	v_fmac_f32_e32 v246, v11, v226
	v_fmac_f32_e32 v247, v11, v227
	v_fmac_f32_e32 v248, v11, v228
	v_fmac_f32_e32 v249, v11, v229
	v_fmac_f32_e32 v246, v12, v230
	v_fmac_f32_e32 v247, v12, v231
	v_fmac_f32_e32 v248, v12, v232
	v_fmac_f32_e32 v249, v12, v233
	v_fmac_f32_e32 v246, v13, v234
	v_fmac_f32_e32 v247, v13, v235
	v_fmac_f32_e32 v248, v13, v236
	v_fmac_f32_e32 v249, v13, v237
	v_fmac_f32_e32 v246, v14, v238
	v_fmac_f32_e32 v247, v14, v239
	v_fmac_f32_e32 v248, v14, v240
	v_fmac_f32_e32 v249, v14, v241
	v_fmac_f32_e32 v246, v15, v242
	v_fmac_f32_e32 v247, v15, v243
	v_fmac_f32_e32 v248, v15, v244
	v_fmac_f32_e32 v249, v15, v245
	v_add_f32_dpp v246, v246, v246 quad_perm:[1,0,3,2] row_mask:0xf bank_mask:0xf
	v_add_f32_dpp v247, v247, v247 quad_perm:[1,0,3,2] row_mask:0xf bank_mask:0xf
	v_add_f32_dpp v248, v248, v248 quad_perm:[1,0,3,2] row_mask:0xf bank_mask:0xf
	v_add_f32_dpp v249, v249, v249 quad_perm:[1,0,3,2] row_mask:0xf bank_mask:0xf
	v_add_f32_dpp v246, v246, v246 quad_perm:[2,3,0,1] row_mask:0xf bank_mask:0xf
	v_add_f32_dpp v247, v247, v247 quad_perm:[2,3,0,1] row_mask:0xf bank_mask:0xf
	v_add_f32_dpp v248, v248, v248 quad_perm:[2,3,0,1] row_mask:0xf bank_mask:0xf
	v_add_f32_dpp v249, v249, v249 quad_perm:[2,3,0,1] row_mask:0xf bank_mask:0xf
	s_mov_b64 exec, s[2:3]
	ds_write_b128 v153, v[246:249]
	s_mov_b64 exec, -1
	s_waitcnt vmcnt(8)
	v_mul_f32_e32 v246, v16, v148
	v_mul_f32_e32 v247, v16, v149
	v_mul_f32_e32 v248, v16, v150
	v_mul_f32_e32 v249, v16, v151
	v_fmac_f32_e32 v246, v17, v154
	v_fmac_f32_e32 v247, v17, v155
	v_fmac_f32_e32 v248, v17, v156
	v_fmac_f32_e32 v249, v17, v157
	v_fmac_f32_e32 v246, v18, v158
	v_fmac_f32_e32 v247, v18, v159
	v_fmac_f32_e32 v248, v18, v160
	v_fmac_f32_e32 v249, v18, v161
	v_fmac_f32_e32 v246, v19, v162
	v_fmac_f32_e32 v247, v19, v163
	v_fmac_f32_e32 v248, v19, v164
	v_fmac_f32_e32 v249, v19, v165
	v_fmac_f32_e32 v246, v20, v194
	v_fmac_f32_e32 v247, v20, v195
	v_fmac_f32_e32 v248, v20, v196
	v_fmac_f32_e32 v249, v20, v197
	v_fmac_f32_e32 v246, v21, v198
	v_fmac_f32_e32 v247, v21, v199
	v_fmac_f32_e32 v248, v21, v200
	v_fmac_f32_e32 v249, v21, v201
	v_fmac_f32_e32 v246, v22, v202
	v_fmac_f32_e32 v247, v22, v203
	v_fmac_f32_e32 v248, v22, v204
	v_fmac_f32_e32 v249, v22, v205
	v_fmac_f32_e32 v246, v23, v210
	v_fmac_f32_e32 v247, v23, v211
	v_fmac_f32_e32 v248, v23, v212
	v_fmac_f32_e32 v249, v23, v213
	v_fmac_f32_e32 v246, v24, v214
	v_fmac_f32_e32 v247, v24, v215
	v_fmac_f32_e32 v248, v24, v216
	v_fmac_f32_e32 v249, v24, v217
	v_fmac_f32_e32 v246, v25, v218
	v_fmac_f32_e32 v247, v25, v219
	v_fmac_f32_e32 v248, v25, v220
	v_fmac_f32_e32 v249, v25, v221
	v_fmac_f32_e32 v246, v26, v222
	v_fmac_f32_e32 v247, v26, v223
	v_fmac_f32_e32 v248, v26, v224
	v_fmac_f32_e32 v249, v26, v225
	v_fmac_f32_e32 v246, v27, v226
	v_fmac_f32_e32 v247, v27, v227
	v_fmac_f32_e32 v248, v27, v228
	v_fmac_f32_e32 v249, v27, v229
	v_fmac_f32_e32 v246, v28, v230
	v_fmac_f32_e32 v247, v28, v231
	v_fmac_f32_e32 v248, v28, v232
	v_fmac_f32_e32 v249, v28, v233
	v_fmac_f32_e32 v246, v29, v234
	v_fmac_f32_e32 v247, v29, v235
	v_fmac_f32_e32 v248, v29, v236
	v_fmac_f32_e32 v249, v29, v237
	v_fmac_f32_e32 v246, v30, v238
	v_fmac_f32_e32 v247, v30, v239
	v_fmac_f32_e32 v248, v30, v240
	v_fmac_f32_e32 v249, v30, v241
	v_fmac_f32_e32 v246, v31, v242
	v_fmac_f32_e32 v247, v31, v243
	v_fmac_f32_e32 v248, v31, v244
	v_fmac_f32_e32 v249, v31, v245
	v_add_f32_dpp v246, v246, v246 quad_perm:[1,0,3,2] row_mask:0xf bank_mask:0xf
	v_add_f32_dpp v247, v247, v247 quad_perm:[1,0,3,2] row_mask:0xf bank_mask:0xf
	v_add_f32_dpp v248, v248, v248 quad_perm:[1,0,3,2] row_mask:0xf bank_mask:0xf
	v_add_f32_dpp v249, v249, v249 quad_perm:[1,0,3,2] row_mask:0xf bank_mask:0xf
	v_add_f32_dpp v246, v246, v246 quad_perm:[2,3,0,1] row_mask:0xf bank_mask:0xf
	v_add_f32_dpp v247, v247, v247 quad_perm:[2,3,0,1] row_mask:0xf bank_mask:0xf
	v_add_f32_dpp v248, v248, v248 quad_perm:[2,3,0,1] row_mask:0xf bank_mask:0xf
	v_add_f32_dpp v249, v249, v249 quad_perm:[2,3,0,1] row_mask:0xf bank_mask:0xf
	s_mov_b64 exec, s[2:3]
	ds_write_b128 v153, v[246:249] offset:256
	s_mov_b64 exec, -1
	s_waitcnt vmcnt(4)
; template <int L, int N> DEVQ void filt_item(const Params& P, LAS unsigned char* lds, const float* H3v, int d, cf* specd, float* cornerd) {
;     ...
;     for (int k = tid; k < L; k += NTHR) {
;         asm volatile("" ::: "memory");
;         const f32x4* hr = (const f32x4*)(H3v + (size_t)k * 64);
;         f32x4 acc = (f32x4){0.f, 0.f, 0.f, 0.f};
;         f32x4 hv[16];
; #pragma unroll
;         for (int i4 = 0; i4 < 16; ++i4) hv[i4] = hr[i4];
; #pragma unroll
;         for (int i4 = 0; i4 < 16; ++i4) { if ((i4 & 3) == 0) asm volatile("" ::: "memory");
;             acc += hv[i4].x * wc4[4 * i4] + hv[i4].y * wc4[4 * i4 + 1] + hv[i4].z * wc4[4 * i4 + 2] + hv[i4].w * wc4[4 * i4 + 3]; }
;         const float dec = expf(-((float)k / (float)(L - 1)) * delta);
;         acc *= dec;
;         if (k <= N / 2) X[swz(k)] = cf{acc.x * invN, acc.z * invN};
	v_mul_f32_e32 v246, v32, v148
	v_mul_f32_e32 v247, v32, v149
	v_mul_f32_e32 v248, v32, v150
	v_mul_f32_e32 v249, v32, v151
	v_fmac_f32_e32 v246, v33, v154
	v_fmac_f32_e32 v247, v33, v155
	v_fmac_f32_e32 v248, v33, v156
	v_fmac_f32_e32 v249, v33, v157
	v_fmac_f32_e32 v246, v34, v158
	v_fmac_f32_e32 v247, v34, v159
	v_fmac_f32_e32 v248, v34, v160
	v_fmac_f32_e32 v249, v34, v161
	v_fmac_f32_e32 v246, v35, v162
	v_fmac_f32_e32 v247, v35, v163
	v_fmac_f32_e32 v248, v35, v164
	v_fmac_f32_e32 v249, v35, v165
	v_fmac_f32_e32 v246, v36, v194
	v_fmac_f32_e32 v247, v36, v195
	v_fmac_f32_e32 v248, v36, v196
	v_fmac_f32_e32 v249, v36, v197
	v_fmac_f32_e32 v246, v37, v198
	v_fmac_f32_e32 v247, v37, v199
	v_fmac_f32_e32 v248, v37, v200
	v_fmac_f32_e32 v249, v37, v201
	v_fmac_f32_e32 v246, v38, v202
	v_fmac_f32_e32 v247, v38, v203
	v_fmac_f32_e32 v248, v38, v204
	v_fmac_f32_e32 v249, v38, v205
	v_fmac_f32_e32 v246, v39, v210
	v_fmac_f32_e32 v247, v39, v211
	v_fmac_f32_e32 v248, v39, v212
	v_fmac_f32_e32 v249, v39, v213
	v_fmac_f32_e32 v246, v40, v214
	v_fmac_f32_e32 v247, v40, v215
	v_fmac_f32_e32 v248, v40, v216
	v_fmac_f32_e32 v249, v40, v217
	v_fmac_f32_e32 v246, v41, v218
	v_fmac_f32_e32 v247, v41, v219
	v_fmac_f32_e32 v248, v41, v220
	v_fmac_f32_e32 v249, v41, v221
	v_fmac_f32_e32 v246, v42, v222
	v_fmac_f32_e32 v247, v42, v223
	v_fmac_f32_e32 v248, v42, v224
	v_fmac_f32_e32 v249, v42, v225
	v_fmac_f32_e32 v246, v43, v226
	v_fmac_f32_e32 v247, v43, v227
	v_fmac_f32_e32 v248, v43, v228
	v_fmac_f32_e32 v249, v43, v229
	v_fmac_f32_e32 v246, v44, v230
	v_fmac_f32_e32 v247, v44, v231
	v_fmac_f32_e32 v248, v44, v232
	v_fmac_f32_e32 v249, v44, v233
	v_fmac_f32_e32 v246, v45, v234
	v_fmac_f32_e32 v247, v45, v235
	v_fmac_f32_e32 v248, v45, v236
	v_fmac_f32_e32 v249, v45, v237
	v_fmac_f32_e32 v246, v46, v238
	v_fmac_f32_e32 v247, v46, v239
	v_fmac_f32_e32 v248, v46, v240
	v_fmac_f32_e32 v249, v46, v241
	v_fmac_f32_e32 v246, v47, v242
	v_fmac_f32_e32 v247, v47, v243
	v_fmac_f32_e32 v248, v47, v244
	v_fmac_f32_e32 v249, v47, v245
	v_add_f32_dpp v246, v246, v246 quad_perm:[1,0,3,2] row_mask:0xf bank_mask:0xf
	v_add_f32_dpp v247, v247, v247 quad_perm:[1,0,3,2] row_mask:0xf bank_mask:0xf
	v_add_f32_dpp v248, v248, v248 quad_perm:[1,0,3,2] row_mask:0xf bank_mask:0xf
	v_add_f32_dpp v249, v249, v249 quad_perm:[1,0,3,2] row_mask:0xf bank_mask:0xf
	v_add_f32_dpp v246, v246, v246 quad_perm:[2,3,0,1] row_mask:0xf bank_mask:0xf
	v_add_f32_dpp v247, v247, v247 quad_perm:[2,3,0,1] row_mask:0xf bank_mask:0xf
	v_add_f32_dpp v248, v248, v248 quad_perm:[2,3,0,1] row_mask:0xf bank_mask:0xf
	v_add_f32_dpp v249, v249, v249 quad_perm:[2,3,0,1] row_mask:0xf bank_mask:0xf
	s_mov_b64 exec, s[2:3]
	ds_write_b128 v153, v[246:249] offset:512
	s_mov_b64 exec, -1
	s_waitcnt vmcnt(0)
	v_mul_f32_e32 v246, v48, v148
	v_mul_f32_e32 v247, v48, v149
	v_mul_f32_e32 v248, v48, v150
	v_mul_f32_e32 v249, v48, v151
	v_fmac_f32_e32 v246, v49, v154
	v_fmac_f32_e32 v247, v49, v155
	v_fmac_f32_e32 v248, v49, v156
	v_fmac_f32_e32 v249, v49, v157
	v_fmac_f32_e32 v246, v50, v158
	v_fmac_f32_e32 v247, v50, v159
	v_fmac_f32_e32 v248, v50, v160
	v_fmac_f32_e32 v249, v50, v161
	v_fmac_f32_e32 v246, v51, v162
	v_fmac_f32_e32 v247, v51, v163
	v_fmac_f32_e32 v248, v51, v164
	v_fmac_f32_e32 v249, v51, v165
	v_fmac_f32_e32 v246, v52, v194
	v_fmac_f32_e32 v247, v52, v195
	v_fmac_f32_e32 v248, v52, v196
	v_fmac_f32_e32 v249, v52, v197
	v_fmac_f32_e32 v246, v53, v198
	v_fmac_f32_e32 v247, v53, v199
	v_fmac_f32_e32 v248, v53, v200
	v_fmac_f32_e32 v249, v53, v201
	v_fmac_f32_e32 v246, v54, v202
	v_fmac_f32_e32 v247, v54, v203
	v_fmac_f32_e32 v248, v54, v204
	v_fmac_f32_e32 v249, v54, v205
	v_fmac_f32_e32 v246, v55, v210
	v_fmac_f32_e32 v247, v55, v211
	v_fmac_f32_e32 v248, v55, v212
	v_fmac_f32_e32 v249, v55, v213
	v_fmac_f32_e32 v246, v56, v214
	v_fmac_f32_e32 v247, v56, v215
	v_fmac_f32_e32 v248, v56, v216
	v_fmac_f32_e32 v249, v56, v217
	v_fmac_f32_e32 v246, v57, v218
	v_fmac_f32_e32 v247, v57, v219
	v_fmac_f32_e32 v248, v57, v220
	v_fmac_f32_e32 v249, v57, v221
	v_fmac_f32_e32 v246, v58, v222
	v_fmac_f32_e32 v247, v58, v223
	v_fmac_f32_e32 v248, v58, v224
	v_fmac_f32_e32 v249, v58, v225
	v_fmac_f32_e32 v246, v59, v226
	v_fmac_f32_e32 v247, v59, v227
	v_fmac_f32_e32 v248, v59, v228
	v_fmac_f32_e32 v249, v59, v229
	v_fmac_f32_e32 v246, v60, v230
	v_fmac_f32_e32 v247, v60, v231
	v_fmac_f32_e32 v248, v60, v232
	v_fmac_f32_e32 v249, v60, v233
	v_fmac_f32_e32 v246, v61, v234
	v_fmac_f32_e32 v247, v61, v235
	v_fmac_f32_e32 v248, v61, v236
	v_fmac_f32_e32 v249, v61, v237
	v_fmac_f32_e32 v246, v62, v238
	v_fmac_f32_e32 v247, v62, v239
	v_fmac_f32_e32 v248, v62, v240
	v_fmac_f32_e32 v249, v62, v241
	v_fmac_f32_e32 v246, v63, v242
	v_fmac_f32_e32 v247, v63, v243
	v_fmac_f32_e32 v248, v63, v244
	v_fmac_f32_e32 v249, v63, v245
	v_add_f32_dpp v246, v246, v246 quad_perm:[1,0,3,2] row_mask:0xf bank_mask:0xf
	v_add_f32_dpp v247, v247, v247 quad_perm:[1,0,3,2] row_mask:0xf bank_mask:0xf
	v_add_f32_dpp v248, v248, v248 quad_perm:[1,0,3,2] row_mask:0xf bank_mask:0xf
	v_add_f32_dpp v249, v249, v249 quad_perm:[1,0,3,2] row_mask:0xf bank_mask:0xf
	v_add_f32_dpp v246, v246, v246 quad_perm:[2,3,0,1] row_mask:0xf bank_mask:0xf
	v_add_f32_dpp v247, v247, v247 quad_perm:[2,3,0,1] row_mask:0xf bank_mask:0xf
	v_add_f32_dpp v248, v248, v248 quad_perm:[2,3,0,1] row_mask:0xf bank_mask:0xf
	v_add_f32_dpp v249, v249, v249 quad_perm:[2,3,0,1] row_mask:0xf bank_mask:0xf
	s_mov_b64 exec, s[2:3]
	ds_write_b128 v153, v[246:249] offset:768
	s_mov_b64 exec, -1
	s_waitcnt lgkmcnt(0)
	ds_read_b128 v[0:3], v193
	s_mov_b32 s11, 0xc5807800
	v_cvt_f32_i32_e32 v4, v75
	s_waitcnt lgkmcnt(0)
	s_mov_b64 exec, s[14:15]
	v_div_scale_f32 v5, s[2:3], s11, s11, v4
	v_rcp_f32_e32 v6, v5
	s_mov_b32 s2, 0xc2ce8ed0
	v_fma_f32 v7, -v5, v6, 1.0
	v_fmac_f32_e32 v6, v7, v6
	v_div_scale_f32 v7, vcc, v4, s11, v4
	v_mul_f32_e32 v8, v7, v6
	v_fma_f32 v9, -v5, v8, v7
	v_fmac_f32_e32 v8, v9, v6
	v_fma_f32 v5, -v5, v8, v7
	v_div_fmas_f32 v5, v5, v6, v8
	v_div_fixup_f32 v4, v5, s11, v4
	v_mul_f32_e64 v4, |v74|, v4
	v_mul_f32_e32 v5, 0x3fb8aa3b, v4
	v_fma_f32 v6, v4, s18, -v5
	v_rndne_f32_e32 v7, v5
	v_fmac_f32_e32 v6, 0x32a5705f, v4
	v_sub_f32_e32 v5, v5, v7
	v_add_f32_e32 v5, v5, v6
	v_exp_f32_e32 v5, v5
	v_cvt_i32_f32_e32 v6, v7
	v_cmp_ngt_f32_e32 vcc, s2, v4
	s_mov_b32 s2, 0x42b17218
	v_ldexp_f32 v5, v5, v6
	v_cndmask_b32_e32 v5, 0, v5, vcc
	v_cmp_nlt_f32_e32 vcc, s2, v4
	s_movk_i32 s2, 0x1001
	s_nop 0
	v_cndmask_b32_e32 v4, v188, v5, vcc
	v_pk_mul_f32 v[0:1], v[4:5], v[0:1] op_sel_hi:[0,1]
	v_pk_mul_f32 v[2:3], v[4:5], v[2:3] op_sel_hi:[0,1]
	v_cmp_gt_i32_e32 vcc, s2, v75
	s_and_saveexec_b64 s[14:15], vcc
	s_cbranch_execz .LBB0_593
	v_ashrrev_i32_e32 v6, 5, v75
	v_lshlrev_b32_e32 v7, 2, v6
	v_and_b32_e32 v7, 28, v7
	v_and_b32_e32 v6, 3, v6
	v_mov_b32_e32 v4, v0
	v_mov_b32_e32 v5, v2
	s_mov_b32 s2, 0x39000000
	v_bitop3_b32 v6, v7, v75, v6 bitop3:0x36
	v_pk_mul_f32 v[4:5], v[4:5], s[2:3] op_sel_hi:[1,0]
	v_lshl_add_u32 v6, v6, 3, 0
	ds_write_b64 v6, v[4:5]

; template <int L, int N> DEVQ void filt_item(const Params& P, LAS unsigned char* lds, const float* H3v, int d, cf* specd, float* cornerd) {
;     ...
;     const float delta = fabsf(MIN_DECAY + (float)d * ((MAX_DECAY - MIN_DECAY) / 1023.0f));
;     const float invN = 1.0f / (float)N;
;     for (int k = tid; k < L; k += NTHR) {
;         asm volatile("" ::: "memory");
;         const f32x4* hr = (const f32x4*)(H3v + (size_t)k * 64);
;         f32x4 acc = (f32x4){0.f, 0.f, 0.f, 0.f};
;         f32x4 hv[16];
; #pragma unroll
;         for (int i4 = 0; i4 < 16; ++i4) hv[i4] = hr[i4];
; #pragma unroll
;         for (int i4 = 0; i4 < 16; ++i4) { if ((i4 & 3) == 0) asm volatile("" ::: "memory");
;             acc += hv[i4].x * wc4[4 * i4] + hv[i4].y * wc4[4 * i4 + 1] + hv[i4].z * wc4[4 * i4 + 2] + hv[i4].w * wc4[4 * i4 + 3]; }
.LBB0_624:
	s_or_b64 exec, exec, s[0:1]
	s_movk_i32 s0, 0x2010
	v_cmp_gt_i32_e32 vcc, s0, v64
	s_waitcnt lgkmcnt(0)
	s_barrier
	s_and_saveexec_b64 s[0:1], vcc
	s_cbranch_execz .LBB0_633
	s_waitcnt vmcnt(0)
	v_cvt_f32_i32_e32 v2, s12
	v_readlane_b32 s2, v254, 32
	v_lshlrev_b64 v[0:1], 8, v[64:65]
	v_mov_b32_e32 v3, 0xc0447cbd
	v_lshl_add_u32 v72, v64, 2, s2
	v_sub_u32_e32 v73, 0x4000, v64
	v_fmamk_f32 v74, v2, 0xbc44ade8, v3
	v_lshl_add_u64 v[66:67], s[6:7], 0, v[0:1]
	s_mov_b64 s[14:15], 0
	v_mov_b32_e32 v75, v64
	v_mbcnt_lo_u32_b32 v193, -1, 0
	v_mbcnt_hi_u32_b32 v193, -1, v193
	v_lshrrev_b32_e32 v246, 2, v193
	v_and_b32_e32 v247, 3, v193
	v_lshlrev_b32_e32 v248, 8, v246
	v_lshl_add_u32 v248, v247, 4, v248
	v_lshlrev_b32_e32 v249, 8, v193
	v_sub_u32_e32 v248, v248, v249
	v_add_u32_e32 v250, 0x1000, v248
	v_ashrrev_i32_e32 v251, 31, v250
	v_lshl_add_u32 v248, v247, 6, 0
	v_add_u32_e32 v248, 0x20000, v248
	ds_read_b128 v[148:151], v248
	ds_read_b128 v[154:157], v248 offset:16
	ds_read_b128 v[158:161], v248 offset:32
	ds_read_b128 v[162:165], v248 offset:48
	ds_read_b128 v[194:197], v248 offset:256
	ds_read_b128 v[198:201], v248 offset:272
	ds_read_b128 v[202:205], v248 offset:288
	ds_read_b128 v[210:213], v248 offset:304
	ds_read_b128 v[214:217], v248 offset:512
	ds_read_b128 v[218:221], v248 offset:528
	ds_read_b128 v[222:225], v248 offset:544
	ds_read_b128 v[226:229], v248 offset:560
	ds_read_b128 v[230:233], v248 offset:768
	ds_read_b128 v[234:237], v248 offset:784
	ds_read_b128 v[238:241], v248 offset:800
	ds_read_b128 v[242:245], v248 offset:816
	v_lshrrev_b32_e32 v249, 6, v64
	v_cmp_lt_u32_e64 s[2:3], 5, v249
	v_lshl_add_u32 v249, v249, 10, 0
	v_mov_b32_e32 v247, 0x400
	v_add_u32_e32 v249, 0x20800, v249
	v_cndmask_b32_e64 v247, 0, v247, s[2:3]
	v_add_u32_e32 v249, v249, v247
	v_lshl_add_u32 v153, v246, 4, v249
	v_lshl_add_u32 v193, v193, 4, v249
	s_waitcnt lgkmcnt(0)
	s_branch .LBB0_627

; template <int L, int N> DEVQ void filt_item(const Params& P, LAS unsigned char* lds, const float* H3v, int d, cf* specd, float* cornerd) {
;     ...
;     for (int k = tid; k < L; k += NTHR) {
;         asm volatile("" ::: "memory");
;         const f32x4* hr = (const f32x4*)(H3v + (size_t)k * 64);
;         f32x4 acc = (f32x4){0.f, 0.f, 0.f, 0.f};
;         f32x4 hv[16];
; #pragma unroll
;         for (int i4 = 0; i4 < 16; ++i4) hv[i4] = hr[i4];
; #pragma unroll
;         for (int i4 = 0; i4 < 16; ++i4) { if ((i4 & 3) == 0) asm volatile("" ::: "memory");
;             acc += hv[i4].x * wc4[4 * i4] + hv[i4].y * wc4[4 * i4 + 1] + hv[i4].z * wc4[4 * i4 + 2] + hv[i4].w * wc4[4 * i4 + 3]; }
.LBB0_627:
	s_mov_b64 s[20:21], exec
	s_mov_b64 exec, -1
	v_lshl_add_u64 v[180:181], v[66:67], 0, v[250:251]
	v_add_co_u32_e32 v206, vcc, 0x2000, v180
	s_nop 1
	v_addc_co_u32_e32 v207, vcc, 0, v181, vcc
	global_load_dwordx4 v[0:3], v[180:181], off offset:-4096
	global_load_dwordx4 v[4:7], v[180:181], off offset:-4032
	global_load_dwordx4 v[8:11], v[180:181], off offset:-3968
	global_load_dwordx4 v[12:15], v[180:181], off offset:-3904
	global_load_dwordx4 v[16:19], v[180:181], off offset:0
	global_load_dwordx4 v[20:23], v[180:181], off offset:64
	global_load_dwordx4 v[24:27], v[180:181], off offset:128
	global_load_dwordx4 v[28:31], v[180:181], off offset:192
	global_load_dwordx4 v[32:35], v[206:207], off offset:-4096
	global_load_dwordx4 v[36:39], v[206:207], off offset:-4032
	global_load_dwordx4 v[40:43], v[206:207], off offset:-3968
	global_load_dwordx4 v[44:47], v[206:207], off offset:-3904
	global_load_dwordx4 v[48:51], v[206:207], off offset:0
	global_load_dwordx4 v[52:55], v[206:207], off offset:64
	global_load_dwordx4 v[56:59], v[206:207], off offset:128
	global_load_dwordx4 v[60:63], v[206:207], off offset:192
	s_mov_b32 s2, 0x11111111
	s_mov_b32 s3, 0x11111111
	s_waitcnt vmcnt(12)
	v_mul_f32_e32 v246, v0, v148
	v_mul_f32_e32 v247, v0, v149
	v_mul_f32_e32 v248, v0, v150
	v_mul_f32_e32 v249, v0, v151
	v_fmac_f32_e32 v246, v1, v154
	v_fmac_f32_e32 v247, v1, v155
	v_fmac_f32_e32 v248, v1, v156
	v_fmac_f32_e32 v249, v1, v157
	v_fmac_f32_e32 v246, v2, v158
	v_fmac_f32_e32 v247, v2, v159
	v_fmac_f32_e32 v248, v2, v160
	v_fmac_f32_e32 v249, v2, v161
	v_fmac_f32_e32 v246, v3, v162
	v_fmac_f32_e32 v247, v3, v163
	v_fmac_f32_e32 v248, v3, v164
	v_fmac_f32_e32 v249, v3, v165
	v_fmac_f32_e32 v246, v4, v194
	v_fmac_f32_e32 v247, v4, v195
	v_fmac_f32_e32 v248, v4, v196
	v_fmac_f32_e32 v249, v4, v197
	v_fmac_f32_e32 v246, v5, v198
	v_fmac_f32_e32 v247, v5, v199
	v_fmac_f32_e32 v248, v5, v200
	v_fmac_f32_e32 v249, v5, v201
	v_fmac_f32_e32 v246, v6, v202
	v_fmac_f32_e32 v247, v6, v203
	v_fmac_f32_e32 v248, v6, v204
	v_fmac_f32_e32 v249, v6, v205
	v_fmac_f32_e32 v246, v7, v210
	v_fmac_f32_e32 v247, v7, v211
	v_fmac_f32_e32 v248, v7, v212
	v_fmac_f32_e32 v249, v7, v213
	v_fmac_f32_e32 v246, v8, v214
	v_fmac_f32_e32 v247, v8, v215
	v_fmac_f32_e32 v248, v8, v216
	v_fmac_f32_e32 v249, v8, v217
	v_fmac_f32_e32 v246, v9, v218
	v_fmac_f32_e32 v247, v9, v219
	v_fmac_f32_e32 v248, v9, v220
	v_fmac_f32_e32 v249, v9, v221
	v_fmac_f32_e32 v246, v10, v222
	v_fmac_f32_e32 v247, v10, v223
	v_fmac_f32_e32 v248, v10, v224
	v_fmac_f32_e32 v249, v10, v225
	v_fmac_f32_e32 v246, v11, v226
	v_fmac_f32_e32 v247, v11, v227
	v_fmac_f32_e32 v248, v11, v228
	v_fmac_f32_e32 v249, v11, v229
	v_fmac_f32_e32 v246, v12, v230
	v_fmac_f32_e32 v247, v12, v231
	v_fmac_f32_e32 v248, v12, v232
	v_fmac_f32_e32 v249, v12, v233
	v_fmac_f32_e32 v246, v13, v234
	v_fmac_f32_e32 v247, v13, v235
	v_fmac_f32_e32 v248, v13, v236
	v_fmac_f32_e32 v249, v13, v237
	v_fmac_f32_e32 v246, v14, v238
	v_fmac_f32_e32 v247, v14, v239
	v_fmac_f32_e32 v248, v14, v240
	v_fmac_f32_e32 v249, v14, v241
	v_fmac_f32_e32 v246, v15, v242
	v_fmac_f32_e32 v247, v15, v243
	v_fmac_f32_e32 v248, v15, v244
	v_fmac_f32_e32 v249, v15, v245
	v_add_f32_dpp v246, v246, v246 quad_perm:[1,0,3,2] row_mask:0xf bank_mask:0xf
	v_add_f32_dpp v247, v247, v247 quad_perm:[1,0,3,2] row_mask:0xf bank_mask:0xf
	v_add_f32_dpp v248, v248, v248 quad_perm:[1,0,3,2] row_mask:0xf bank_mask:0xf
	v_add_f32_dpp v249, v249, v249 quad_perm:[1,0,3,2] row_mask:0xf bank_mask:0xf
	v_add_f32_dpp v246, v246, v246 quad_perm:[2,3,0,1] row_mask:0xf bank_mask:0xf
	v_add_f32_dpp v247, v247, v247 quad_perm:[2,3,0,1] row_mask:0xf bank_mask:0xf
	v_add_f32_dpp v248, v248, v248 quad_perm:[2,3,0,1] row_mask:0xf bank_mask:0xf
	v_add_f32_dpp v249, v249, v249 quad_perm:[2,3,0,1] row_mask:0xf bank_mask:0xf
	s_mov_b64 exec, s[2:3]
	ds_write_b128 v153, v[246:249]
	s_mov_b64 exec, -1
	s_waitcnt vmcnt(8)
	v_mul_f32_e32 v246, v16, v148
	v_mul_f32_e32 v247, v16, v149
	v_mul_f32_e32 v248, v16, v150
	v_mul_f32_e32 v249, v16, v151
	v_fmac_f32_e32 v246, v17, v154
	v_fmac_f32_e32 v247, v17, v155
	v_fmac_f32_e32 v248, v17, v156
	v_fmac_f32_e32 v249, v17, v157
	v_fmac_f32_e32 v246, v18, v158
	v_fmac_f32_e32 v247, v18, v159
	v_fmac_f32_e32 v248, v18, v160
	v_fmac_f32_e32 v249, v18, v161
	v_fmac_f32_e32 v246, v19, v162
	v_fmac_f32_e32 v247, v19, v163
	v_fmac_f32_e32 v248, v19, v164
	v_fmac_f32_e32 v249, v19, v165
	v_fmac_f32_e32 v246, v20, v194
	v_fmac_f32_e32 v247, v20, v195
	v_fmac_f32_e32 v248, v20, v196
	v_fmac_f32_e32 v249, v20, v197
	v_fmac_f32_e32 v246, v21, v198
	v_fmac_f32_e32 v247, v21, v199
	v_fmac_f32_e32 v248, v21, v200
	v_fmac_f32_e32 v249, v21, v201
	v_fmac_f32_e32 v246, v22, v202
	v_fmac_f32_e32 v247, v22, v203
	v_fmac_f32_e32 v248, v22, v204
	v_fmac_f32_e32 v249, v22, v205
	v_fmac_f32_e32 v246, v23, v210
	v_fmac_f32_e32 v247, v23, v211
	v_fmac_f32_e32 v248, v23, v212
	v_fmac_f32_e32 v249, v23, v213
	v_fmac_f32_e32 v246, v24, v214
	v_fmac_f32_e32 v247, v24, v215
	v_fmac_f32_e32 v248, v24, v216
	v_fmac_f32_e32 v249, v24, v217
	v_fmac_f32_e32 v246, v25, v218
	v_fmac_f32_e32 v247, v25, v219
	v_fmac_f32_e32 v248, v25, v220
	v_fmac_f32_e32 v249, v25, v221
	v_fmac_f32_e32 v246, v26, v222
	v_fmac_f32_e32 v247, v26, v223
	v_fmac_f32_e32 v248, v26, v224
	v_fmac_f32_e32 v249, v26, v225
	v_fmac_f32_e32 v246, v27, v226
	v_fmac_f32_e32 v247, v27, v227
	v_fmac_f32_e32 v248, v27, v228
	v_fmac_f32_e32 v249, v27, v229
	v_fmac_f32_e32 v246, v28, v230
	v_fmac_f32_e32 v247, v28, v231
	v_fmac_f32_e32 v248, v28, v232
	v_fmac_f32_e32 v249, v28, v233
	v_fmac_f32_e32 v246, v29, v234
	v_fmac_f32_e32 v247, v29, v235
	v_fmac_f32_e32 v248, v29, v236
	v_fmac_f32_e32 v249, v29, v237
	v_fmac_f32_e32 v246, v30, v238
	v_fmac_f32_e32 v247, v30, v239
	v_fmac_f32_e32 v248, v30, v240
	v_fmac_f32_e32 v249, v30, v241
	v_fmac_f32_e32 v246, v31, v242
	v_fmac_f32_e32 v247, v31, v243
	v_fmac_f32_e32 v248, v31, v244
	v_fmac_f32_e32 v249, v31, v245
	v_add_f32_dpp v246, v246, v246 quad_perm:[1,0,3,2] row_mask:0xf bank_mask:0xf
	v_add_f32_dpp v247, v247, v247 quad_perm:[1,0,3,2] row_mask:0xf bank_mask:0xf
	v_add_f32_dpp v248, v248, v248 quad_perm:[1,0,3,2] row_mask:0xf bank_mask:0xf
	v_add_f32_dpp v249, v249, v249 quad_perm:[1,0,3,2] row_mask:0xf bank_mask:0xf
	v_add_f32_dpp v246, v246, v246 quad_perm:[2,3,0,1] row_mask:0xf bank_mask:0xf
	v_add_f32_dpp v247, v247, v247 quad_perm:[2,3,0,1] row_mask:0xf bank_mask:0xf
	v_add_f32_dpp v248, v248, v248 quad_perm:[2,3,0,1] row_mask:0xf bank_mask:0xf
	v_add_f32_dpp v249, v249, v249 quad_perm:[2,3,0,1] row_mask:0xf bank_mask:0xf
	s_mov_b64 exec, s[2:3]
	ds_write_b128 v153, v[246:249] offset:256
	s_mov_b64 exec, -1
	s_waitcnt vmcnt(4)
; template <int L, int N> DEVQ void filt_item(const Params& P, LAS unsigned char* lds, const float* H3v, int d, cf* specd, float* cornerd) {
;     ...
;     for (int k = tid; k < L; k += NTHR) {
;         asm volatile("" ::: "memory");
;         const f32x4* hr = (const f32x4*)(H3v + (size_t)k * 64);
;         f32x4 acc = (f32x4){0.f, 0.f, 0.f, 0.f};
;         f32x4 hv[16];
; #pragma unroll
;         for (int i4 = 0; i4 < 16; ++i4) hv[i4] = hr[i4];
; #pragma unroll
;         for (int i4 = 0; i4 < 16; ++i4) { if ((i4 & 3) == 0) asm volatile("" ::: "memory");
;             acc += hv[i4].x * wc4[4 * i4] + hv[i4].y * wc4[4 * i4 + 1] + hv[i4].z * wc4[4 * i4 + 2] + hv[i4].w * wc4[4 * i4 + 3]; }
;         const float dec = expf(-((float)k / (float)(L - 1)) * delta);
;         acc *= dec;
;         if (k <= N / 2) X[swz(k)] = cf{acc.x * invN, acc.z * invN};
	v_mul_f32_e32 v246, v32, v148
	v_mul_f32_e32 v247, v32, v149
	v_mul_f32_e32 v248, v32, v150
	v_mul_f32_e32 v249, v32, v151
	v_fmac_f32_e32 v246, v33, v154
	v_fmac_f32_e32 v247, v33, v155
	v_fmac_f32_e32 v248, v33, v156
	v_fmac_f32_e32 v249, v33, v157
	v_fmac_f32_e32 v246, v34, v158
	v_fmac_f32_e32 v247, v34, v159
	v_fmac_f32_e32 v248, v34, v160
	v_fmac_f32_e32 v249, v34, v161
	v_fmac_f32_e32 v246, v35, v162
	v_fmac_f32_e32 v247, v35, v163
	v_fmac_f32_e32 v248, v35, v164
	v_fmac_f32_e32 v249, v35, v165
	v_fmac_f32_e32 v246, v36, v194
	v_fmac_f32_e32 v247, v36, v195
	v_fmac_f32_e32 v248, v36, v196
	v_fmac_f32_e32 v249, v36, v197
	v_fmac_f32_e32 v246, v37, v198
	v_fmac_f32_e32 v247, v37, v199
	v_fmac_f32_e32 v248, v37, v200
	v_fmac_f32_e32 v249, v37, v201
	v_fmac_f32_e32 v246, v38, v202
	v_fmac_f32_e32 v247, v38, v203
	v_fmac_f32_e32 v248, v38, v204
	v_fmac_f32_e32 v249, v38, v205
	v_fmac_f32_e32 v246, v39, v210
	v_fmac_f32_e32 v247, v39, v211
	v_fmac_f32_e32 v248, v39, v212
	v_fmac_f32_e32 v249, v39, v213
	v_fmac_f32_e32 v246, v40, v214
	v_fmac_f32_e32 v247, v40, v215
	v_fmac_f32_e32 v248, v40, v216
	v_fmac_f32_e32 v249, v40, v217
	v_fmac_f32_e32 v246, v41, v218
	v_fmac_f32_e32 v247, v41, v219
	v_fmac_f32_e32 v248, v41, v220
	v_fmac_f32_e32 v249, v41, v221
	v_fmac_f32_e32 v246, v42, v222
	v_fmac_f32_e32 v247, v42, v223
	v_fmac_f32_e32 v248, v42, v224
	v_fmac_f32_e32 v249, v42, v225
	v_fmac_f32_e32 v246, v43, v226
	v_fmac_f32_e32 v247, v43, v227
	v_fmac_f32_e32 v248, v43, v228
	v_fmac_f32_e32 v249, v43, v229
	v_fmac_f32_e32 v246, v44, v230
	v_fmac_f32_e32 v247, v44, v231
	v_fmac_f32_e32 v248, v44, v232
	v_fmac_f32_e32 v249, v44, v233
	v_fmac_f32_e32 v246, v45, v234
	v_fmac_f32_e32 v247, v45, v235
	v_fmac_f32_e32 v248, v45, v236
	v_fmac_f32_e32 v249, v45, v237
	v_fmac_f32_e32 v246, v46, v238
	v_fmac_f32_e32 v247, v46, v239
	v_fmac_f32_e32 v248, v46, v240
	v_fmac_f32_e32 v249, v46, v241
	v_fmac_f32_e32 v246, v47, v242
	v_fmac_f32_e32 v247, v47, v243
	v_fmac_f32_e32 v248, v47, v244
	v_fmac_f32_e32 v249, v47, v245
	v_add_f32_dpp v246, v246, v246 quad_perm:[1,0,3,2] row_mask:0xf bank_mask:0xf
	v_add_f32_dpp v247, v247, v247 quad_perm:[1,0,3,2] row_mask:0xf bank_mask:0xf
	v_add_f32_dpp v248, v248, v248 quad_perm:[1,0,3,2] row_mask:0xf bank_mask:0xf
	v_add_f32_dpp v249, v249, v249 quad_perm:[1,0,3,2] row_mask:0xf bank_mask:0xf
	v_add_f32_dpp v246, v246, v246 quad_perm:[2,3,0,1] row_mask:0xf bank_mask:0xf
	v_add_f32_dpp v247, v247, v247 quad_perm:[2,3,0,1] row_mask:0xf bank_mask:0xf
	v_add_f32_dpp v248, v248, v248 quad_perm:[2,3,0,1] row_mask:0xf bank_mask:0xf
	v_add_f32_dpp v249, v249, v249 quad_perm:[2,3,0,1] row_mask:0xf bank_mask:0xf
	s_mov_b64 exec, s[2:3]
	ds_write_b128 v153, v[246:249] offset:512
	s_mov_b64 exec, -1
	s_waitcnt vmcnt(0)
	v_mul_f32_e32 v246, v48, v148
	v_mul_f32_e32 v247, v48, v149
	v_mul_f32_e32 v248, v48, v150
	v_mul_f32_e32 v249, v48, v151
	v_fmac_f32_e32 v246, v49, v154
	v_fmac_f32_e32 v247, v49, v155
	v_fmac_f32_e32 v248, v49, v156
	v_fmac_f32_e32 v249, v49, v157
	v_fmac_f32_e32 v246, v50, v158
	v_fmac_f32_e32 v247, v50, v159
	v_fmac_f32_e32 v248, v50, v160
	v_fmac_f32_e32 v249, v50, v161
	v_fmac_f32_e32 v246, v51, v162
	v_fmac_f32_e32 v247, v51, v163
	v_fmac_f32_e32 v248, v51, v164
	v_fmac_f32_e32 v249, v51, v165
	v_fmac_f32_e32 v246, v52, v194
	v_fmac_f32_e32 v247, v52, v195
	v_fmac_f32_e32 v248, v52, v196
	v_fmac_f32_e32 v249, v52, v197
	v_fmac_f32_e32 v246, v53, v198
	v_fmac_f32_e32 v247, v53, v199
	v_fmac_f32_e32 v248, v53, v200
	v_fmac_f32_e32 v249, v53, v201
	v_fmac_f32_e32 v246, v54, v202
	v_fmac_f32_e32 v247, v54, v203
	v_fmac_f32_e32 v248, v54, v204
	v_fmac_f32_e32 v249, v54, v205
	v_fmac_f32_e32 v246, v55, v210
	v_fmac_f32_e32 v247, v55, v211
	v_fmac_f32_e32 v248, v55, v212
	v_fmac_f32_e32 v249, v55, v213
	v_fmac_f32_e32 v246, v56, v214
	v_fmac_f32_e32 v247, v56, v215
	v_fmac_f32_e32 v248, v56, v216
	v_fmac_f32_e32 v249, v56, v217
	v_fmac_f32_e32 v246, v57, v218
	v_fmac_f32_e32 v247, v57, v219
	v_fmac_f32_e32 v248, v57, v220
	v_fmac_f32_e32 v249, v57, v221
	v_fmac_f32_e32 v246, v58, v222
	v_fmac_f32_e32 v247, v58, v223
	v_fmac_f32_e32 v248, v58, v224
	v_fmac_f32_e32 v249, v58, v225
	v_fmac_f32_e32 v246, v59, v226
	v_fmac_f32_e32 v247, v59, v227
	v_fmac_f32_e32 v248, v59, v228
	v_fmac_f32_e32 v249, v59, v229
	v_fmac_f32_e32 v246, v60, v230
	v_fmac_f32_e32 v247, v60, v231
	v_fmac_f32_e32 v248, v60, v232
	v_fmac_f32_e32 v249, v60, v233
	v_fmac_f32_e32 v246, v61, v234
	v_fmac_f32_e32 v247, v61, v235
	v_fmac_f32_e32 v248, v61, v236
	v_fmac_f32_e32 v249, v61, v237
	v_fmac_f32_e32 v246, v62, v238
	v_fmac_f32_e32 v247, v62, v239
	v_fmac_f32_e32 v248, v62, v240
	v_fmac_f32_e32 v249, v62, v241
	v_fmac_f32_e32 v246, v63, v242
	v_fmac_f32_e32 v247, v63, v243
	v_fmac_f32_e32 v248, v63, v244
	v_fmac_f32_e32 v249, v63, v245
	v_add_f32_dpp v246, v246, v246 quad_perm:[1,0,3,2] row_mask:0xf bank_mask:0xf
	v_add_f32_dpp v247, v247, v247 quad_perm:[1,0,3,2] row_mask:0xf bank_mask:0xf
	v_add_f32_dpp v248, v248, v248 quad_perm:[1,0,3,2] row_mask:0xf bank_mask:0xf
	v_add_f32_dpp v249, v249, v249 quad_perm:[1,0,3,2] row_mask:0xf bank_mask:0xf
	v_add_f32_dpp v246, v246, v246 quad_perm:[2,3,0,1] row_mask:0xf bank_mask:0xf
	v_add_f32_dpp v247, v247, v247 quad_perm:[2,3,0,1] row_mask:0xf bank_mask:0xf
	v_add_f32_dpp v248, v248, v248 quad_perm:[2,3,0,1] row_mask:0xf bank_mask:0xf
	v_add_f32_dpp v249, v249, v249 quad_perm:[2,3,0,1] row_mask:0xf bank_mask:0xf
	s_mov_b64 exec, s[2:3]
	ds_write_b128 v153, v[246:249] offset:768
	s_mov_b64 exec, -1
	s_waitcnt lgkmcnt(0)
	ds_read_b128 v[0:3], v193
	v_cvt_f32_i32_e32 v4, v75
	s_waitcnt lgkmcnt(0)
	s_mov_b64 exec, s[20:21]
	v_div_scale_f32 v5, s[2:3], s23, s23, v4
	v_rcp_f32_e32 v6, v5
	s_mov_b32 s2, 0xc2ce8ed0
	v_fma_f32 v7, -v5, v6, 1.0
	v_fmac_f32_e32 v6, v7, v6
	v_div_scale_f32 v7, vcc, v4, s23, v4
	v_mul_f32_e32 v8, v7, v6
	v_fma_f32 v9, -v5, v8, v7
	v_fmac_f32_e32 v8, v9, v6
	v_fma_f32 v5, -v5, v8, v7
	v_div_fmas_f32 v5, v5, v6, v8
	v_div_fixup_f32 v4, v5, s23, v4
	v_mul_f32_e64 v4, |v74|, v4
	v_mul_f32_e32 v5, 0x3fb8aa3b, v4
	v_fma_f32 v6, v4, s18, -v5
	v_rndne_f32_e32 v7, v5
	v_fmac_f32_e32 v6, 0x32a5705f, v4
	v_sub_f32_e32 v5, v5, v7
	v_add_f32_e32 v5, v5, v6
	v_exp_f32_e32 v5, v5
	v_cvt_i32_f32_e32 v6, v7
	v_cmp_ngt_f32_e32 vcc, s2, v4
	s_mov_b32 s2, 0x42b17218
	v_ldexp_f32 v5, v5, v6
	v_cndmask_b32_e32 v5, 0, v5, vcc
	v_cmp_nlt_f32_e32 vcc, s2, v4
	s_movk_i32 s2, 0x2001
	s_nop 0
	v_cndmask_b32_e32 v4, v188, v5, vcc
	v_pk_mul_f32 v[0:1], v[4:5], v[0:1] op_sel_hi:[0,1]
	v_pk_mul_f32 v[2:3], v[4:5], v[2:3] op_sel_hi:[0,1]
	v_cmp_gt_i32_e32 vcc, s2, v75
	s_and_saveexec_b64 s[20:21], vcc
	s_cbranch_execz .LBB0_629
	v_ashrrev_i32_e32 v6, 5, v75
	v_lshlrev_b32_e32 v7, 2, v6
	v_and_b32_e32 v7, 28, v7
	v_and_b32_e32 v6, 3, v6
	v_mov_b32_e32 v4, v0
	v_mov_b32_e32 v5, v2
	s_mov_b32 s2, 0x38800000
	v_bitop3_b32 v6, v7, v75, v6 bitop3:0x36
	v_pk_mul_f32 v[4:5], v[4:5], s[2:3] op_sel_hi:[1,0]
	v_lshl_add_u32 v6, v6, 3, 0
	ds_write_b64 v6, v[4:5]
